# prologue: modulation GEMV items moved to workgroups 64..255 so the 32 S5-table workgroups skip them
# speedup vs baseline: 1.0117x; 1.0024x over previous
.LBB0_13:
	v_writelane_b32 v253, s16, 8
	s_nop 1
	v_writelane_b32 v253, s17, 9
	v_writelane_b32 v253, s18, 10
	v_writelane_b32 v253, s19, 11
	v_writelane_b32 v253, s20, 12
	v_writelane_b32 v253, s21, 13
	v_writelane_b32 v253, s22, 14
	v_writelane_b32 v253, s23, 15
	v_writelane_b32 v253, s24, 16
	v_writelane_b32 v253, s25, 17
	v_writelane_b32 v253, s26, 18
	v_writelane_b32 v253, s27, 19
	v_writelane_b32 v253, s28, 20
	v_writelane_b32 v253, s29, 21
	v_writelane_b32 v253, s30, 22
	v_writelane_b32 v253, s31, 23
	s_or_b64 exec, exec, s[2:3]
	s_load_dwordx16 s[52:67], s[0:1], 0x40
	s_load_dwordx16 s[4:19], s[0:1], 0x80
	s_cmpk_lt_i32 s80, 0x40
	s_waitcnt lgkmcnt(0)
	s_barrier
	v_writelane_b32 v253, s4, 24
	s_nop 1
	v_writelane_b32 v253, s5, 25
	v_writelane_b32 v253, s6, 26
	v_writelane_b32 v253, s7, 27
	v_writelane_b32 v253, s8, 28
	v_writelane_b32 v253, s9, 29
	v_writelane_b32 v253, s10, 30
	v_writelane_b32 v253, s11, 31
	v_writelane_b32 v253, s12, 32
	v_writelane_b32 v253, s13, 33
	v_writelane_b32 v253, s14, 34
	v_writelane_b32 v253, s15, 35
	v_writelane_b32 v253, s16, 36
	v_writelane_b32 v253, s17, 37
	v_writelane_b32 v253, s18, 38
	v_writelane_b32 v253, s19, 39
	s_cbranch_scc1 .LBB0_20
	v_and_b32_e32 v2, 63, v8
	v_readlane_b32 s0, v253, 8
	v_ashrrev_i32_e32 v4, 6, v8
	v_readlane_b32 s8, v253, 16
	v_readlane_b32 s9, v253, 17
	v_readlane_b32 s10, v253, 18
	v_lshlrev_b32_e32 v3, 2, v2
	s_movk_i32 s0, 0x300
	v_readlane_b32 s1, v253, 9
	v_readlane_b32 s11, v253, 19
	v_readlane_b32 s12, v253, 20
	v_readlane_b32 s13, v253, 21
	v_readlane_b32 s14, v253, 22
	v_readlane_b32 s15, v253, 23
	v_mov_b32_e32 v10, s8
	v_mov_b32_e32 v11, s9
	v_add_u32_e32 v6, 0, v3
	v_lshlrev_b32_e32 v5, 7, v4
	v_mul_lo_u32 v7, v4, s0
	s_movk_i32 s0, 0xc0
	v_lshlrev_b32_e32 v12, 8, v4
	s_movk_i32 s10, 0x3000
	v_add_u32_e32 v1, v6, v7
	v_add3_u32 v3, 0, v7, v3
	v_cmp_gt_i32_e32 vcc, s0, v8
	v_mov_b32_e32 v7, 0
	v_mad_i64_i32 v[10:11], s[0:1], v5, s10, v[10:11]
	v_lshl_add_u32 v5, v4, 9, 0
	v_mov_b32_e32 v9, 0xc00000
	s_movk_i32 s11, 0x6000
	s_mov_b32 s12, 0x9000
	s_mov_b32 s13, 0xc000
	s_mov_b32 s14, 0xf000
	s_mov_b32 s15, 0x12000
	s_mov_b32 s16, 0x15000
	s_mov_b32 s17, 0x18000
	s_mov_b32 s18, 0x1b000
	s_mov_b32 s19, 0x1e000
	s_mov_b32 s20, 0x21000
	s_mov_b32 s21, 0x24000
	s_mov_b32 s22, 0x27000
	s_mov_b32 s23, 0x2a000
	s_mov_b32 s24, 0x2d000
	v_add_u32_e32 v16, v6, v12
	v_lshlrev_b32_e32 v6, 2, v2
	s_sub_i32 s25, s80, 64
	v_readlane_b32 s2, v253, 10
	v_readlane_b32 s3, v253, 11
	v_readlane_b32 s4, v253, 12
	v_readlane_b32 s5, v253, 13
	v_readlane_b32 s6, v253, 14
	v_readlane_b32 s7, v253, 15
	s_branch .LBB0_16
